# bundle plus P0 transpose tiles rebalanced toward the 64 workgroups without an adaLN task
# speedup vs baseline: 1.0109x; 1.0035x over previous
.LBB0_21:
	s_cmpk_gt_i32 s92, 0xc7f
	s_barrier
	s_cbranch_scc1 .LBB0_40
	s_add_u32 s3, s94, 0x5400000
	s_addc_u32 s10, s95, 0
	s_add_u32 s11, s94, 0x3c00000
	s_addc_u32 s12, s95, 0
	s_lshl_b32 s0, s92, 8
	s_add_i32 s13, s0, 0xfff58000
	s_lshl_b32 s14, s30, 8
	s_lshl_b32 s15, s92, 3
	s_lshl_b32 s16, s30, 3
	s_mov_b32 s1, 0
	v_mov_b32_e32 v5, 0
	s_movk_i32 s17, 0x204
	s_mov_b32 s18, 0x5040100
	s_mov_b32 s19, 0xf000
	s_mov_b32 s20, s92
	s_mov_b32 s24, 0
	s_branch .LBB0_24
.LBB0_23:
	s_add_i32 s24, s24, 1
	s_cmp_lt_u32 s24, 10
	s_cbranch_scc0 .Ltrb_late
	s_lshl_b32 s25, s24, 8
	s_add_i32 s20, s92, s25
	s_branch .Ltrb_set
.Ltrb_late:
	s_cmp_lt_u32 s92, 0xc0
	s_cbranch_scc0 .Ltrb_free
	s_cmp_eq_u32 s24, 10
	s_cbranch_scc0 .LBB0_40
	s_add_i32 s20, s92, 0xbc0
	s_branch .Ltrb_set
.Ltrb_free:
	s_cmp_gt_u32 s24, 16
	s_cbranch_scc1 .LBB0_40
	s_sub_i32 s25, s24, 10
	s_lshl_b32 s25, s25, 6
	s_add_i32 s20, s92, s25
	s_add_i32 s20, s20, 0x940
.Ltrb_set:
	s_lshl_b32 s13, s20, 8
	s_add_i32 s13, s13, 0xfff58000
	s_lshl_b32 s15, s20, 3
	s_cmpk_gt_i32 s20, 0xc7f
	s_cbranch_scc1 .LBB0_40
